# P3 loop: five bf16 packs moved from the LDS-loaded PV gaps 3-7 to gaps 12-15 (on top of the deferred-row-sum variant)
# baseline (speedup 1.0000x reference)
.LBB0_327:
	s_waitcnt lgkmcnt(4)
	v_mfma_f32_32x32x16_bf16 v[48:63], v[182:185], v[174:177], v[48:63]
	v_add_f32_e32 v190, v255, v80
	v_exp_f32_e32 v190, v190
	ds_read_b64_tr_b16 v[246:247], v158 offset:36864
	ds_read_b64_tr_b16 v[248:249], v158 offset:38912
	v_add_f32_e32 v157, v190, v96
	v_mfma_f32_32x32x16_bf16 v[32:47], v[178:181], v[174:177], v[32:47]
	v_add_f32_e32 v191, v255, v81
	v_exp_f32_e32 v191, v191
	ds_read_b64_tr_b16 v[250:251], v159 offset:36864
	ds_read_b64_tr_b16 v[252:253], v159 offset:38912
	v_add_f32_e32 v156, v191, v97
	v_add_f32_e32 v157, v156, v157
	s_waitcnt lgkmcnt(4)
	v_mfma_f32_32x32x16_bf16 v[16:31], v[148:151], v[174:177], v[16:31]
	v_add_f32_e32 v192, v255, v82
	v_exp_f32_e32 v192, v192
	ds_read_b64_tr_b16 v[182:183], v160 offset:36864
	ds_read_b64_tr_b16 v[184:185], v160 offset:38912
	v_add_f32_e32 v156, v192, v98
	v_add_f32_e32 v157, v156, v157
	v_mfma_f32_32x32x16_bf16 v[0:15], v[152:155], v[174:177], v[0:15]
	v_add_f32_e32 v193, v255, v83
	v_exp_f32_e32 v193, v193
	ds_read_b64_tr_b16 v[178:179], v161 offset:36864
	ds_read_b64_tr_b16 v[180:181], v161 offset:38912
	v_add_f32_e32 v156, v193, v99
	v_add_f32_e32 v157, v156, v157
	s_waitcnt lgkmcnt(4)
	v_mfma_f32_32x32x16_bf16 v[48:63], v[246:249], v[162:165], v[48:63]
	v_add_f32_e32 v194, v255, v84
	v_exp_f32_e32 v194, v194
	ds_read_b64_tr_b16 v[148:149], v158 offset:40960
	ds_read_b64_tr_b16 v[150:151], v158 offset:43008
	v_add_f32_e32 v156, v194, v100
	v_add_f32_e32 v157, v156, v157
	v_mfma_f32_32x32x16_bf16 v[32:47], v[250:253], v[162:165], v[32:47]
	v_add_f32_e32 v195, v255, v85
	v_exp_f32_e32 v195, v195
	ds_read_b64_tr_b16 v[152:153], v159 offset:40960
	ds_read_b64_tr_b16 v[154:155], v159 offset:43008
	v_add_f32_e32 v156, v195, v101
	v_add_f32_e32 v157, v156, v157
	s_waitcnt lgkmcnt(4)
	v_mfma_f32_32x32x16_bf16 v[16:31], v[182:185], v[162:165], v[16:31]
	v_add_f32_e32 v196, v255, v86
	v_exp_f32_e32 v196, v196
	ds_read_b64_tr_b16 v[246:247], v160 offset:40960
	ds_read_b64_tr_b16 v[248:249], v160 offset:43008
	v_add_f32_e32 v156, v196, v102
	v_add_f32_e32 v157, v156, v157
	v_mfma_f32_32x32x16_bf16 v[0:15], v[178:181], v[162:165], v[0:15]
	v_add_f32_e32 v197, v255, v87
	v_exp_f32_e32 v197, v197
	ds_read_b64_tr_b16 v[250:251], v161 offset:40960
	ds_read_b64_tr_b16 v[252:253], v161 offset:43008
	v_add_f32_e32 v156, v197, v103
	v_add_f32_e32 v157, v156, v157
	s_waitcnt lgkmcnt(4)
	v_mfma_f32_32x32x16_bf16 v[48:63], v[148:151], v[170:173], v[48:63]
	v_add_f32_e32 v198, v255, v88
	v_exp_f32_e32 v198, v198
	ds_read_b64_tr_b16 v[182:183], v158 offset:45056
	ds_read_b64_tr_b16 v[184:185], v158 offset:47104
	v_add_f32_e32 v157, v104, v157
	v_cvt_pk_bf16_f32 v163, v106, v107
	v_mfma_f32_32x32x16_bf16 v[32:47], v[152:155], v[170:173], v[32:47]
	v_add_f32_e32 v199, v255, v89
	v_exp_f32_e32 v199, v199
	ds_read_b64_tr_b16 v[178:179], v159 offset:45056
	ds_read_b64_tr_b16 v[180:181], v159 offset:47104
	v_add_f32_e32 v157, v105, v157
	v_cvt_pk_bf16_f32 v164, v108, v109
	s_waitcnt lgkmcnt(4)
	v_mfma_f32_32x32x16_bf16 v[16:31], v[246:249], v[170:173], v[16:31]
	v_add_f32_e32 v200, v255, v90
	v_exp_f32_e32 v200, v200
	ds_read_b64_tr_b16 v[148:149], v160 offset:45056
	ds_read_b64_tr_b16 v[150:151], v160 offset:47104
	v_add_f32_e32 v157, v106, v157
	v_cvt_pk_bf16_f32 v165, v110, v111
	v_mfma_f32_32x32x16_bf16 v[0:15], v[250:253], v[170:173], v[0:15]
	v_add_f32_e32 v201, v255, v91
	v_exp_f32_e32 v201, v201
	ds_read_b64_tr_b16 v[152:153], v161 offset:45056
	ds_read_b64_tr_b16 v[154:155], v161 offset:47104
	v_add_f32_e32 v157, v107, v157
	v_cvt_pk_bf16_f32 v170, v190, v191
	s_waitcnt lgkmcnt(4)
	v_mfma_f32_32x32x16_bf16 v[48:63], v[182:185], v[166:169], v[48:63]
	v_add_f32_e32 v202, v255, v92
	v_exp_f32_e32 v202, v202
	v_cvt_pk_bf16_f32 v171, v192, v193
	v_cvt_pk_bf16_f32 v174, v96, v97
	v_add_f32_e32 v157, v108, v157
	v_mfma_f32_32x32x16_bf16 v[32:47], v[178:181], v[166:169], v[32:47]
	v_add_f32_e32 v203, v255, v93
	v_exp_f32_e32 v203, v203
	v_cvt_pk_bf16_f32 v172, v194, v195
	v_cvt_pk_bf16_f32 v175, v98, v99
	v_add_f32_e32 v157, v109, v157
	s_waitcnt lgkmcnt(0)
	v_mfma_f32_32x32x16_bf16 v[16:31], v[148:151], v[166:169], v[16:31]
	v_add_f32_e32 v204, v255, v94
	v_exp_f32_e32 v204, v204
	v_cvt_pk_bf16_f32 v173, v196, v197
	v_cvt_pk_bf16_f32 v176, v100, v101
	v_add_f32_e32 v157, v110, v157
	v_mfma_f32_32x32x16_bf16 v[0:15], v[152:155], v[166:169], v[0:15]
	v_add_f32_e32 v205, v255, v95
	v_exp_f32_e32 v205, v205
	v_add_f32_e32 v157, v111, v157
	v_cvt_pk_bf16_f32 v177, v102, v103
	v_cvt_pk_bf16_f32 v162, v104, v105
	s_add_i32 s72, s72, 1
	s_add_i32 s79, s79, 0x8000
	s_add_i32 s100, s100, 64
	v_add_f32_e32 v229, v229, v157
	v_lshl_add_u64 v[218:219], v[218:219], 0, s[88:89]
	v_lshl_add_u64 v[220:221], v[220:221], 0, s[88:89]
	v_lshl_add_u64 v[224:225], v[224:225], 0, s[92:93]
	s_and_b32 s1, s79, 0x18000
	s_xor_b32 s0, s1, 0x10000
	v_add_u32_e32 v85, s0, v222
	v_add_u32_e32 v254, s0, v223
	v_add_u32_e32 v255, s0, v241
	v_add_u32_e32 v84, s0, v242
	s_cmp_ge_i32 s72, s99
	s_cbranch_scc1 .LBB0_332
	s_cmp_ge_i32 s72, s73
	s_cbranch_scc1 .Lk_last
	s_waitcnt vmcnt(4) lgkmcnt(0)
	s_barrier
	s_branch .Lk_top
